# k12 plus the mixer-A PV block's first lgkmcnt(0) moved down to its first consumer (past the cvt/permlane pack of P)
# baseline (speedup 1.0000x reference)
; #define SBAR() __builtin_amdgcn_sched_barrier(0)
; template <int D0> __device__ __forceinline__ void pv_one(f32x16& od, int vb, bf16x8 pa0, bf16x8 pa1, bf16x8 pa2, bf16x8 pa3) {
;     const s16x4 l0 = tr_read<v_rd_off(D0, 0, 0)>(vb), h0 = tr_read<v_rd_off(D0, 0, 1)>(vb), l1 = tr_read<v_rd_off(D0, 1, 0)>(vb), h1 = tr_read<v_rd_off(D0, 1, 1)>(vb);
;     const s16x4 l2 = tr_read<v_rd_off(D0, 2, 0)>(vb), h2 = tr_read<v_rd_off(D0, 2, 1)>(vb), l3 = tr_read<v_rd_off(D0, 3, 0)>(vb), h3 = tr_read<v_rd_off(D0, 3, 1)>(vb);
;     asm volatile("s_waitcnt lgkmcnt(0)" ::: "memory"); SBAR();
;     ...
;     od = __builtin_amdgcn_mfma_f32_32x32x16_bf16(pa0, PK(l0, h0), od, 0, 0, 0);
;     od = __builtin_amdgcn_mfma_f32_32x32x16_bf16(pa1, PK(l1, h1), od, 0, 0, 0);
;     od = __builtin_amdgcn_mfma_f32_32x32x16_bf16(pa2, PK(l2, h2), od, 0, 0, 0);
;     od = __builtin_amdgcn_mfma_f32_32x32x16_bf16(pa3, PK(l3, h3), od, 0, 0, 0);
;     ...
; }
; template <int MODE>
; __device__ __forceinline__ void flash_core(const bf16_t* __restrict__ Qg, const bf16_t* __restrict__ Kg, const bf16_t* __restrict__ Vg,
;                                            int jlo, int jhi, int wlo, int whi, int qpos0, float slope2, char* lds, f32x16 (&o)[4], float& l_out) {
;     ...
;             bf16x8 pa0, pa1, pa2, pa3;
;     ...
;             PK4(p0, 0, pa0); PK4(p0, 8, pa1); PK4(p1, 0, pa2); PK4(p1, 8, pa3);
;     ...
;             pv_one<0>(o[0], vb, pa0, pa1, pa2, pa3); pv_one<1>(o[1], vb, pa0, pa1, pa2, pa3);
;             pv_one<2>(o[2], vb, pa0, pa1, pa2, pa3); pv_one<3>(o[3], vb, pa0, pa1, pa2, pa3);
.LBB0_411:
	v_add_u32_e32 v107, s30, v200
	v_cvt_pk_bf16_f32 v80, v80, v81
	v_cvt_pk_bf16_f32 v81, v82, v83
	v_cvt_pk_bf16_f32 v82, v84, v85
	v_cvt_pk_bf16_f32 v85, v91, v92
	v_cvt_pk_bf16_f32 v91, v6, v7
	ds_read_b64_tr_b16 v[6:7], v107 offset:0
	v_cvt_pk_bf16_f32 v83, v86, v89
	v_cvt_pk_bf16_f32 v86, v93, v94
	v_cvt_pk_bf16_f32 v93, v2, v11
	v_cvt_pk_bf16_f32 v2, v3, v8
	v_cvt_pk_bf16_f32 v3, v9, v14
	ds_read_b64_tr_b16 v[8:9], v107 offset:0x800
	v_cvt_pk_bf16_f32 v84, v87, v90
	v_cvt_pk_bf16_f32 v90, v0, v10
	ds_read_b64_tr_b16 v[10:11], v107 offset:0x1000
	v_cvt_pk_bf16_f32 v92, v4, v5
	v_cvt_pk_bf16_f32 v4, v12, v13
	ds_read_b64_tr_b16 v[12:13], v107 offset:0x1800
	v_add_f32_e32 v106, v98, v99
	v_cvt_pk_bf16_f32 v87, v95, v96
	ds_read_b64_tr_b16 v[94:95], v107 offset:0x2000
	v_fmac_f32_e32 v106, v203, v97
	ds_read_b64_tr_b16 v[96:97], v107 offset:0x2800
	ds_read_b64_tr_b16 v[98:99], v107 offset:0x3000
	ds_read_b64_tr_b16 v[100:101], v107 offset:0x3800
	v_cvt_pk_bf16_f32 v5, v15, v88
	v_permlane32_swap_b32_e32 v80, v82
	v_permlane32_swap_b32_e32 v81, v83
	v_permlane32_swap_b32_e32 v84, v86
	v_permlane32_swap_b32_e32 v85, v87
	v_permlane32_swap_b32_e32 v90, v92
	v_permlane32_swap_b32_e32 v91, v93
	v_permlane32_swap_b32_e32 v2, v4
	v_permlane32_swap_b32_e32 v3, v5
	s_waitcnt lgkmcnt(0)
	v_mfma_f32_32x32x16_bf16 v[64:79], v[80:83], v[6:9], v[64:79]
	ds_read_b64_tr_b16 v[6:7], v107 offset:0x200
	ds_read_b64_tr_b16 v[8:9], v107 offset:0xa00
	v_mfma_f32_32x32x16_bf16 v[64:79], v[84:87], v[10:13], v[64:79]
	ds_read_b64_tr_b16 v[10:11], v107 offset:0x1200
	ds_read_b64_tr_b16 v[12:13], v107 offset:0x1a00
	v_mfma_f32_32x32x16_bf16 v[64:79], v[90:93], v[94:97], v[64:79]
	ds_read_b64_tr_b16 v[94:95], v107 offset:0x2200
	ds_read_b64_tr_b16 v[96:97], v107 offset:0x2a00
	ds_read_b64_tr_b16 v[102:103], v107 offset:0x3200
	ds_read_b64_tr_b16 v[104:105], v107 offset:0x3a00
	v_mfma_f32_32x32x16_bf16 v[64:79], v[2:5], v[98:101], v[64:79]
	s_waitcnt lgkmcnt(6)
	v_mfma_f32_32x32x16_bf16 v[48:63], v[80:83], v[6:9], v[48:63]
	ds_read_b64_tr_b16 v[6:7], v107 offset:0x400
	ds_read_b64_tr_b16 v[8:9], v107 offset:0xc00
	s_waitcnt lgkmcnt(6)
	v_mfma_f32_32x32x16_bf16 v[48:63], v[84:87], v[10:13], v[48:63]
	ds_read_b64_tr_b16 v[10:11], v107 offset:0x1400
	ds_read_b64_tr_b16 v[12:13], v107 offset:0x1c00
	s_waitcnt lgkmcnt(6)
	v_mfma_f32_32x32x16_bf16 v[48:63], v[90:93], v[94:97], v[48:63]
	ds_read_b64_tr_b16 v[94:95], v107 offset:0x2400
	ds_read_b64_tr_b16 v[96:97], v107 offset:0x2c00
	ds_read_b64_tr_b16 v[98:99], v107 offset:0x3400
	ds_read_b64_tr_b16 v[100:101], v107 offset:0x3c00
	s_waitcnt lgkmcnt(8)
	v_mfma_f32_32x32x16_bf16 v[48:63], v[2:5], v[102:105], v[48:63]
	s_waitcnt lgkmcnt(6)
	v_mfma_f32_32x32x16_bf16 v[32:47], v[80:83], v[6:9], v[32:47]
	ds_read_b64_tr_b16 v[6:7], v107 offset:0x600
	ds_read_b64_tr_b16 v[8:9], v107 offset:0xe00
	s_waitcnt lgkmcnt(6)
	v_mfma_f32_32x32x16_bf16 v[32:47], v[84:87], v[10:13], v[32:47]
	ds_read_b64_tr_b16 v[10:11], v107 offset:0x1600
	ds_read_b64_tr_b16 v[12:13], v107 offset:0x1e00
	s_waitcnt lgkmcnt(6)
	v_mfma_f32_32x32x16_bf16 v[32:47], v[90:93], v[94:97], v[32:47]
	ds_read_b64_tr_b16 v[94:95], v107 offset:0x2600
	ds_read_b64_tr_b16 v[96:97], v107 offset:0x2e00
	ds_read_b64_tr_b16 v[102:103], v107 offset:0x3600
	ds_read_b64_tr_b16 v[104:105], v107 offset:0x3e00
	s_waitcnt lgkmcnt(8)
	v_mfma_f32_32x32x16_bf16 v[32:47], v[2:5], v[98:101], v[32:47]
	s_waitcnt lgkmcnt(6)
	v_mfma_f32_32x32x16_bf16 v[16:31], v[80:83], v[6:9], v[16:31]
	v_mov_b32_e32 v203, v106
	s_waitcnt lgkmcnt(4)
	v_mfma_f32_32x32x16_bf16 v[16:31], v[84:87], v[10:13], v[16:31]
	s_waitcnt lgkmcnt(2)
	v_mfma_f32_32x32x16_bf16 v[16:31], v[90:93], v[94:97], v[16:31]
	s_waitcnt lgkmcnt(0)
	v_mfma_f32_32x32x16_bf16 v[16:31], v[2:5], v[102:105], v[16:31]
